# fp8 table build in merge-phase tail: DPP wave-max instead of 6 bpermute hops, 3 row buffers of loads in flight
# baseline (speedup 1.0000x reference)
; __device__ void phase_ffn_norm(const Params& p) {
;     ...
;   unsigned char* q8 = (unsigned char*)(ws + W_F); float* qs = (float*)(ws + W_F + 33554432);
;   for (int r = gw; r < 2 * 16384; r += nw) {
.LBB0_830:
	v_writelane_b32 v244, s10, 0
	v_writelane_b32 v244, s11, 1
	v_writelane_b32 v244, s12, 2
	v_writelane_b32 v244, s13, 3
	v_writelane_b32 v244, s16, 4
	v_writelane_b32 v244, s17, 5
	v_writelane_b32 v244, s18, 6
	v_writelane_b32 v244, s19, 7
	v_writelane_b32 v244, s40, 8
	v_writelane_b32 v244, s41, 9
	v_writelane_b32 v244, s42, 10
	v_writelane_b32 v244, s43, 11
	v_writelane_b32 v244, s44, 12
	v_writelane_b32 v244, s45, 13
	v_writelane_b32 v244, s46, 14
	v_writelane_b32 v244, s47, 15
	v_writelane_b32 v244, s48, 16
	v_writelane_b32 v244, s49, 17
	v_writelane_b32 v244, s50, 18
	v_writelane_b32 v244, s51, 19
	v_writelane_b32 v244, s58, 20
	v_writelane_b32 v244, s59, 21
	v_writelane_b32 v244, s60, 22
	v_writelane_b32 v244, s61, 23
	v_writelane_b32 v244, s62, 24
	v_writelane_b32 v244, s63, 25
	v_writelane_b32 v244, s64, 26
	v_writelane_b32 v244, s65, 27
	v_writelane_b32 v244, s66, 28
	v_writelane_b32 v244, s67, 29
	v_writelane_b32 v244, s68, 30
	v_writelane_b32 v244, s70, 31
	v_writelane_b32 v244, s71, 32
	v_writelane_b32 v244, vcc_lo, 33
	v_writelane_b32 v244, vcc_hi, 34
	s_mov_b64 s[66:67], exec
	s_mov_b64 exec, -1
	s_waitcnt lgkmcnt(0)
	s_barrier
	v_lshlrev_b32_e32 v245, 2, v181
	ds_write_b32 v245, v0 offset:0
	ds_write_b32 v245, v1 offset:1024
	ds_write_b32 v245, v2 offset:2048
	ds_write_b32 v245, v3 offset:3072
	ds_write_b32 v245, v4 offset:4096
	ds_write_b32 v245, v5 offset:5120
	ds_write_b32 v245, v6 offset:6144
	ds_write_b32 v245, v7 offset:7168
	ds_write_b32 v245, v8 offset:8192
	ds_write_b32 v245, v9 offset:9216
	ds_write_b32 v245, v10 offset:10240
	ds_write_b32 v245, v11 offset:11264
	ds_write_b32 v245, v12 offset:12288
	ds_write_b32 v245, v13 offset:13312
	ds_write_b32 v245, v14 offset:14336
	ds_write_b32 v245, v15 offset:15360
	ds_write_b32 v245, v16 offset:16384
	ds_write_b32 v245, v17 offset:17408
	ds_write_b32 v245, v18 offset:18432
	ds_write_b32 v245, v19 offset:19456
	ds_write_b32 v245, v20 offset:20480
	ds_write_b32 v245, v21 offset:21504
	ds_write_b32 v245, v22 offset:22528
	ds_write_b32 v245, v23 offset:23552
	ds_write_b32 v245, v24 offset:24576
	ds_write_b32 v245, v25 offset:25600
	ds_write_b32 v245, v26 offset:26624
	ds_write_b32 v245, v27 offset:27648
	ds_write_b32 v245, v28 offset:28672
	ds_write_b32 v245, v29 offset:29696
	ds_write_b32 v245, v30 offset:30720
	ds_write_b32 v245, v31 offset:31744
	ds_write_b32 v245, v32 offset:32768
	ds_write_b32 v245, v33 offset:33792
	ds_write_b32 v245, v34 offset:34816
	ds_write_b32 v245, v35 offset:35840
	ds_write_b32 v245, v36 offset:36864
	ds_write_b32 v245, v37 offset:37888
	ds_write_b32 v245, v38 offset:38912
	ds_write_b32 v245, v39 offset:39936
	ds_write_b32 v245, v40 offset:40960
	ds_write_b32 v245, v41 offset:41984
	ds_write_b32 v245, v42 offset:43008
	ds_write_b32 v245, v43 offset:44032
	ds_write_b32 v245, v44 offset:45056
	ds_write_b32 v245, v45 offset:46080
	ds_write_b32 v245, v46 offset:47104
	ds_write_b32 v245, v47 offset:48128
	ds_write_b32 v245, v48 offset:49152
	ds_write_b32 v245, v49 offset:50176
	ds_write_b32 v245, v50 offset:51200
	ds_write_b32 v245, v51 offset:52224
	ds_write_b32 v245, v52 offset:53248
	ds_write_b32 v245, v53 offset:54272
	ds_write_b32 v245, v54 offset:55296
	ds_write_b32 v245, v55 offset:56320
	ds_write_b32 v245, v56 offset:57344
	ds_write_b32 v245, v57 offset:58368
	ds_write_b32 v245, v58 offset:59392
	ds_write_b32 v245, v59 offset:60416
	ds_write_b32 v245, v60 offset:61440
	ds_write_b32 v245, v61 offset:62464
	ds_write_b32 v245, v62 offset:63488
	ds_write_b32 v245, v63 offset:64512
	s_waitcnt lgkmcnt(0)
	v_readlane_b32 s40, v248, 33
	v_readfirstlane_b32 s41, v181
	s_nop 1
	s_lshr_b32 s41, s41, 6
	s_cmp_lt_u32 s40, 64
	s_cbranch_scc0 .Lcv_hi
	s_bitcmp1_b32 s40, 0
	s_cbranch_scc1 .Lcv_done
	s_lshr_b32 s40, s40, 1
	s_branch .Lcv_rank

; __device__ void phase_ffn_norm(const Params& p) {
;     ...
;   for (int r = gw; r < 2 * 16384; r += nw) {
;     const float* src = (r < 16384) ? p.in[22] + (size_t)r * DM : p.in[23] + (size_t)(r - 16384) * DM;
;     f32x4 v[4]; float am = 0.f;
; #pragma unroll
;     for (int i = 0; i < 4; ++i) { v[i] = *(const f32x4*)(src + lane * 16 + i * 4); am = fmaxf(am, fmaxf(fmaxf(fabsf(v[i][0]), fabsf(v[i][1])), fmaxf(fabsf(v[i][2]), fabsf(v[i][3])))); }
.Lcv_rank:
	s_lshl_b32 s40, s40, 2
	s_add_i32 s40, s40, s41
	v_readlane_b32 s10, v248, 23
	v_readlane_b32 s11, v248, 24
	v_readlane_b32 s12, v248, 25
	v_readlane_b32 s13, v248, 26
	s_add_u32 s58, s96, 0x1489e000
	s_addc_u32 s59, s97, 0
	v_lshlrev_b32_e32 v0, 6, v180
	v_lshlrev_b32_e32 v1, 4, v180
	v_mov_b32_e32 v9, 0
	v_mov_b32_e32 v8, 0x43600000
	s_and_b32 s41, s40, 0x3fff
	s_cmp_lt_u32 s40, 0x4000
	s_cselect_b32 s60, s10, s12
	s_cselect_b32 s61, s11, s13
	s_cselect_b32 s45, 0, 0x400
	s_lshl_b32 s44, s41, 12
	s_add_u32 s60, s60, s44
	s_addc_u32 s61, s61, 0
	s_lshl_b32 s44, s41, 11
	s_add_i32 s44, s44, s45
	s_add_u32 s46, s58, s44
	s_addc_u32 s47, s59, 0
	s_lshl_b32 s44, s40, 2
	s_add_u32 s48, s58, s44
	s_addc_u32 s49, s59, 0
	s_add_u32 s48, s48, 0x2000000
	s_addc_u32 s49, s49, 0
	global_load_dwordx4 v[16:19], v0, s[60:61]
	global_load_dwordx4 v[20:23], v0, s[60:61] offset:16
	global_load_dwordx4 v[24:27], v0, s[60:61] offset:32
	global_load_dwordx4 v[28:31], v0, s[60:61] offset:48
	s_add_i32 s68, s40, 0x780
	s_and_b32 s41, s68, 0x3fff
	s_cmp_lt_u32 s68, 0x4000
	s_cselect_b32 s60, s10, s12
	s_cselect_b32 s61, s11, s13
	s_cselect_b32 s45, 0, 0x400
	s_lshl_b32 s44, s41, 12
	s_add_u32 s60, s60, s44
	s_addc_u32 s61, s61, 0
	s_lshl_b32 s44, s41, 11
	s_add_i32 s44, s44, s45
	s_add_u32 s62, s58, s44
	s_addc_u32 s63, s59, 0
	s_lshl_b32 s44, s68, 2
	s_add_u32 s64, s58, s44
	s_addc_u32 s65, s59, 0
	s_add_u32 s64, s64, 0x2000000
	s_addc_u32 s65, s65, 0
	global_load_dwordx4 v[32:35], v0, s[60:61]
	global_load_dwordx4 v[36:39], v0, s[60:61] offset:16
	global_load_dwordx4 v[40:43], v0, s[60:61] offset:32
	global_load_dwordx4 v[44:47], v0, s[60:61] offset:48
	s_add_i32 s68, s40, 0xf00
	s_and_b32 s41, s68, 0x3fff
	s_cmp_lt_u32 s68, 0x4000
	s_cselect_b32 s60, s10, s12
	s_cselect_b32 s61, s11, s13
	s_cselect_b32 s45, 0, 0x400
	s_lshl_b32 s44, s41, 12
	s_add_u32 s60, s60, s44
	s_addc_u32 s61, s61, 0
	s_lshl_b32 s44, s41, 11
	s_add_i32 s44, s44, s45
	s_add_u32 s16, s58, s44
	s_addc_u32 s17, s59, 0
	s_lshl_b32 s44, s68, 2
	s_add_u32 s18, s58, s44
	s_addc_u32 s19, s59, 0
	s_add_u32 s18, s18, 0x2000000
	s_addc_u32 s19, s19, 0
	global_load_dwordx4 v[48:51], v0, s[60:61]
	global_load_dwordx4 v[52:55], v0, s[60:61] offset:16
	global_load_dwordx4 v[56:59], v0, s[60:61] offset:32
	global_load_dwordx4 v[60:63], v0, s[60:61] offset:48
.Lcv_loop:
	s_add_i32 s68, s40, 0xf00
	s_cmp_lt_u32 s68, 0x8000
	s_cbranch_scc0 .Lcv_w0_0
	s_waitcnt vmcnt(8)
	s_branch .Lcv_wd_0

; __device__ void phase_ffn_norm(const Params& p) {
;     ...
;     f32x4 v[4]; float am = 0.f;
; #pragma unroll
;     for (int i = 0; i < 4; ++i) { v[i] = *(const f32x4*)(src + lane * 16 + i * 4); am = fmaxf(am, fmaxf(fmaxf(fabsf(v[i][0]), fabsf(v[i][1])), fmaxf(fabsf(v[i][2]), fabsf(v[i][3])))); }
; #pragma unroll
;     for (int o = 32; o >= 1; o >>= 1) am = fmaxf(am, __shfl_xor(am, o));
;     const float sc = am > 0.f ? 224.f / am : 1.f;
;     u32x4 w;
; #pragma unroll
;     for (int i = 0; i < 4; ++i) {
;       int d = 0;
;       d = __builtin_amdgcn_cvt_pk_fp8_f32(v[i][0] * sc, v[i][1] * sc, d, false);
;       d = __builtin_amdgcn_cvt_pk_fp8_f32(v[i][2] * sc, v[i][3] * sc, d, true);
;       w[i] = (unsigned)d;
;     }
;     *(u32x4*)(q8 + (r < 16384 ? (size_t)r * 2048 : (size_t)(r - 16384) * 2048 + 1024) + lane * 16) = w;
;     if (lane == 0) qs[r] = am > 0.f ? am / 224.f : 1.f;
.Lcv_wd_0:
	v_mov_b32_e32 v10, 0
	v_max3_f32 v10, |v16|, |v17|, v10
	v_max3_f32 v10, |v18|, |v19|, v10
	v_max3_f32 v10, |v20|, |v21|, v10
	v_max3_f32 v10, |v22|, |v23|, v10
	v_max3_f32 v10, |v24|, |v25|, v10
	v_max3_f32 v10, |v26|, |v27|, v10
	v_max3_f32 v10, |v28|, |v29|, v10
	v_max3_f32 v10, |v30|, |v31|, v10
	s_nop 1
	v_max_f32_dpp v11, v10, v10 quad_perm:[1,0,3,2] row_mask:0xf bank_mask:0xf
	s_nop 1
	v_max_f32_dpp v10, v11, v11 quad_perm:[2,3,0,1] row_mask:0xf bank_mask:0xf
	s_nop 1
	v_max_f32_dpp v11, v10, v10 row_half_mirror row_mask:0xf bank_mask:0xf
	s_nop 1
	v_max_f32_dpp v10, v11, v11 row_mirror row_mask:0xf bank_mask:0xf
	s_nop 1
	v_max_f32_dpp v10, v10, v10 row_bcast:15 row_mask:0xa bank_mask:0xf
	s_nop 1
	v_max_f32_dpp v10, v10, v10 row_bcast:31 row_mask:0xc bank_mask:0xf
	s_nop 1
	v_readlane_b32 s50, v10, 63
	s_nop 1
	v_mov_b32_e32 v10, s50
	v_div_scale_f32 v11, s[50:51], v10, v10, v8
	v_rcp_f32_e32 v12, v11
	v_div_scale_f32 v13, vcc, v8, v10, v8
	v_cmp_lt_f32_e64 s[70:71], 0, v10
	v_fma_f32 v14, -v11, v12, 1.0
	v_fmac_f32_e32 v12, v14, v12
	v_mul_f32_e32 v14, v13, v12
	v_fma_f32 v15, -v11, v14, v13
	v_fmac_f32_e32 v14, v15, v12
	v_fma_f32 v13, -v11, v14, v13
	v_div_fmas_f32 v13, v13, v12, v14
	v_div_fixup_f32 v13, v13, v10, v8
	v_cndmask_b32_e64 v13, 1.0, v13, s[70:71]
	v_mul_f32_e32 v16, v16, v13
	v_mul_f32_e32 v17, v17, v13
	v_mul_f32_e32 v18, v18, v13
	v_mul_f32_e32 v19, v19, v13
	v_mul_f32_e32 v20, v20, v13
	v_mul_f32_e32 v21, v21, v13
	v_mul_f32_e32 v22, v22, v13
	v_mul_f32_e32 v23, v23, v13
	v_mul_f32_e32 v24, v24, v13
	v_mul_f32_e32 v25, v25, v13
	v_mul_f32_e32 v26, v26, v13
	v_mul_f32_e32 v27, v27, v13
	v_mul_f32_e32 v28, v28, v13
	v_mul_f32_e32 v29, v29, v13
	v_mul_f32_e32 v30, v30, v13
	v_mul_f32_e32 v31, v31, v13
	v_mov_b32_e32 v4, 0
	v_mov_b32_e32 v5, 0
	v_mov_b32_e32 v6, 0
	v_mov_b32_e32 v7, 0
	v_cvt_pk_fp8_f32 v4, v16, v17
	v_cvt_pk_fp8_f32 v5, v20, v21
	v_cvt_pk_fp8_f32 v6, v24, v25
	v_cvt_pk_fp8_f32 v7, v28, v29
	v_cvt_pk_fp8_f32 v4, v18, v19 op_sel:[0,0,1]
	v_cvt_pk_fp8_f32 v5, v22, v23 op_sel:[0,0,1]
	v_cvt_pk_fp8_f32 v6, v26, v27 op_sel:[0,0,1]
	v_cvt_pk_fp8_f32 v7, v30, v31 op_sel:[0,0,1]
	v_div_scale_f32 v11, s[50:51], v8, v8, v10
	v_rcp_f32_e32 v12, v11
	v_div_scale_f32 v13, vcc, v10, v8, v10
	v_fma_f32 v14, -v11, v12, 1.0
	v_fmac_f32_e32 v12, v14, v12
	v_mul_f32_e32 v14, v13, v12
	v_fma_f32 v15, -v11, v14, v13
	v_fmac_f32_e32 v14, v15, v12
	v_fma_f32 v11, -v11, v14, v13
	v_div_fmas_f32 v11, v11, v12, v14
	v_div_fixup_f32 v11, v11, v8, v10
	v_cndmask_b32_e64 v11, 1.0, v11, s[70:71]
	global_store_dwordx4 v1, v[4:7], s[46:47]
	s_mov_b64 exec, 1
	global_store_dword v9, v11, s[48:49]
	s_mov_b64 exec, -1
	s_add_i32 s68, s40, 0x1680
	s_cmp_lt_u32 s68, 0x8000
	s_cbranch_scc0 .Lcv_nl_0
	s_and_b32 s41, s68, 0x3fff
	s_cmp_lt_u32 s68, 0x4000
	s_cselect_b32 s60, s10, s12
	s_cselect_b32 s61, s11, s13
	s_cselect_b32 s45, 0, 0x400
	s_lshl_b32 s44, s41, 12
	s_add_u32 s60, s60, s44
	s_addc_u32 s61, s61, 0
	s_lshl_b32 s44, s41, 11
	s_add_i32 s44, s44, s45
	s_add_u32 s46, s58, s44
	s_addc_u32 s47, s59, 0
	s_lshl_b32 s44, s68, 2
	s_add_u32 s48, s58, s44
	s_addc_u32 s49, s59, 0
	s_add_u32 s48, s48, 0x2000000
	s_addc_u32 s49, s49, 0
	global_load_dwordx4 v[16:19], v0, s[60:61]
	global_load_dwordx4 v[20:23], v0, s[60:61] offset:16
	global_load_dwordx4 v[24:27], v0, s[60:61] offset:32
	global_load_dwordx4 v[28:31], v0, s[60:61] offset:48
.Lcv_nl_0:
	s_add_i32 s40, s40, 0x780
	s_cmp_lt_u32 s40, 0x8000
	s_cbranch_scc0 .Lcv_done
	s_add_i32 s68, s40, 0xf00
	s_cmp_lt_u32 s68, 0x8000
	s_cbranch_scc0 .Lcv_w0_1
	s_waitcnt vmcnt(8)
	s_branch .Lcv_wd_1

; __device__ void phase_ffn_norm(const Params& p) {
;     ...
;     f32x4 v[4]; float am = 0.f;
; #pragma unroll
;     for (int i = 0; i < 4; ++i) { v[i] = *(const f32x4*)(src + lane * 16 + i * 4); am = fmaxf(am, fmaxf(fmaxf(fabsf(v[i][0]), fabsf(v[i][1])), fmaxf(fabsf(v[i][2]), fabsf(v[i][3])))); }
; #pragma unroll
;     for (int o = 32; o >= 1; o >>= 1) am = fmaxf(am, __shfl_xor(am, o));
;     const float sc = am > 0.f ? 224.f / am : 1.f;
;     u32x4 w;
; #pragma unroll
;     for (int i = 0; i < 4; ++i) {
;       int d = 0;
;       d = __builtin_amdgcn_cvt_pk_fp8_f32(v[i][0] * sc, v[i][1] * sc, d, false);
;       d = __builtin_amdgcn_cvt_pk_fp8_f32(v[i][2] * sc, v[i][3] * sc, d, true);
;       w[i] = (unsigned)d;
;     }
;     *(u32x4*)(q8 + (r < 16384 ? (size_t)r * 2048 : (size_t)(r - 16384) * 2048 + 1024) + lane * 16) = w;
;     if (lane == 0) qs[r] = am > 0.f ? am / 224.f : 1.f;
.Lcv_wd_1:
	v_mov_b32_e32 v10, 0
	v_max3_f32 v10, |v32|, |v33|, v10
	v_max3_f32 v10, |v34|, |v35|, v10
	v_max3_f32 v10, |v36|, |v37|, v10
	v_max3_f32 v10, |v38|, |v39|, v10
	v_max3_f32 v10, |v40|, |v41|, v10
	v_max3_f32 v10, |v42|, |v43|, v10
	v_max3_f32 v10, |v44|, |v45|, v10
	v_max3_f32 v10, |v46|, |v47|, v10
	s_nop 1
	v_max_f32_dpp v11, v10, v10 quad_perm:[1,0,3,2] row_mask:0xf bank_mask:0xf
	s_nop 1
	v_max_f32_dpp v10, v11, v11 quad_perm:[2,3,0,1] row_mask:0xf bank_mask:0xf
	s_nop 1
	v_max_f32_dpp v11, v10, v10 row_half_mirror row_mask:0xf bank_mask:0xf
	s_nop 1
	v_max_f32_dpp v10, v11, v11 row_mirror row_mask:0xf bank_mask:0xf
	s_nop 1
	v_max_f32_dpp v10, v10, v10 row_bcast:15 row_mask:0xa bank_mask:0xf
	s_nop 1
	v_max_f32_dpp v10, v10, v10 row_bcast:31 row_mask:0xc bank_mask:0xf
	s_nop 1
	v_readlane_b32 s50, v10, 63
	s_nop 1
	v_mov_b32_e32 v10, s50
	v_div_scale_f32 v11, s[50:51], v10, v10, v8
	v_rcp_f32_e32 v12, v11
	v_div_scale_f32 v13, vcc, v8, v10, v8
	v_cmp_lt_f32_e64 s[70:71], 0, v10
	v_fma_f32 v14, -v11, v12, 1.0
	v_fmac_f32_e32 v12, v14, v12
	v_mul_f32_e32 v14, v13, v12
	v_fma_f32 v15, -v11, v14, v13
	v_fmac_f32_e32 v14, v15, v12
	v_fma_f32 v13, -v11, v14, v13
	v_div_fmas_f32 v13, v13, v12, v14
	v_div_fixup_f32 v13, v13, v10, v8
	v_cndmask_b32_e64 v13, 1.0, v13, s[70:71]
	v_mul_f32_e32 v32, v32, v13
	v_mul_f32_e32 v33, v33, v13
	v_mul_f32_e32 v34, v34, v13
	v_mul_f32_e32 v35, v35, v13
	v_mul_f32_e32 v36, v36, v13
	v_mul_f32_e32 v37, v37, v13
	v_mul_f32_e32 v38, v38, v13
	v_mul_f32_e32 v39, v39, v13
	v_mul_f32_e32 v40, v40, v13
	v_mul_f32_e32 v41, v41, v13
	v_mul_f32_e32 v42, v42, v13
	v_mul_f32_e32 v43, v43, v13
	v_mul_f32_e32 v44, v44, v13
	v_mul_f32_e32 v45, v45, v13
	v_mul_f32_e32 v46, v46, v13
	v_mul_f32_e32 v47, v47, v13
	v_mov_b32_e32 v4, 0
	v_mov_b32_e32 v5, 0
	v_mov_b32_e32 v6, 0
	v_mov_b32_e32 v7, 0
	v_cvt_pk_fp8_f32 v4, v32, v33
	v_cvt_pk_fp8_f32 v5, v36, v37
	v_cvt_pk_fp8_f32 v6, v40, v41
	v_cvt_pk_fp8_f32 v7, v44, v45
	v_cvt_pk_fp8_f32 v4, v34, v35 op_sel:[0,0,1]
	v_cvt_pk_fp8_f32 v5, v38, v39 op_sel:[0,0,1]
	v_cvt_pk_fp8_f32 v6, v42, v43 op_sel:[0,0,1]
	v_cvt_pk_fp8_f32 v7, v46, v47 op_sel:[0,0,1]
	v_div_scale_f32 v11, s[50:51], v8, v8, v10
	v_rcp_f32_e32 v12, v11
	v_div_scale_f32 v13, vcc, v10, v8, v10
	v_fma_f32 v14, -v11, v12, 1.0
	v_fmac_f32_e32 v12, v14, v12
	v_mul_f32_e32 v14, v13, v12
	v_fma_f32 v15, -v11, v14, v13
	v_fmac_f32_e32 v14, v15, v12
	v_fma_f32 v11, -v11, v14, v13
	v_div_fmas_f32 v11, v11, v12, v14
	v_div_fixup_f32 v11, v11, v8, v10
	v_cndmask_b32_e64 v11, 1.0, v11, s[70:71]
	global_store_dwordx4 v1, v[4:7], s[62:63]
	s_mov_b64 exec, 1
	global_store_dword v9, v11, s[64:65]
	s_mov_b64 exec, -1
	s_add_i32 s68, s40, 0x1680
	s_cmp_lt_u32 s68, 0x8000
	s_cbranch_scc0 .Lcv_nl_1
	s_and_b32 s41, s68, 0x3fff
	s_cmp_lt_u32 s68, 0x4000
	s_cselect_b32 s60, s10, s12
	s_cselect_b32 s61, s11, s13
	s_cselect_b32 s45, 0, 0x400
	s_lshl_b32 s44, s41, 12
	s_add_u32 s60, s60, s44
	s_addc_u32 s61, s61, 0
	s_lshl_b32 s44, s41, 11
	s_add_i32 s44, s44, s45
	s_add_u32 s62, s58, s44
	s_addc_u32 s63, s59, 0
	s_lshl_b32 s44, s68, 2
	s_add_u32 s64, s58, s44
	s_addc_u32 s65, s59, 0
	s_add_u32 s64, s64, 0x2000000
	s_addc_u32 s65, s65, 0
	global_load_dwordx4 v[32:35], v0, s[60:61]
	global_load_dwordx4 v[36:39], v0, s[60:61] offset:16
	global_load_dwordx4 v[40:43], v0, s[60:61] offset:32
	global_load_dwordx4 v[44:47], v0, s[60:61] offset:48

; __device__ void phase_ffn_norm(const Params& p) {
;     ...
;     f32x4 v[4]; float am = 0.f;
; #pragma unroll
;     for (int i = 0; i < 4; ++i) { v[i] = *(const f32x4*)(src + lane * 16 + i * 4); am = fmaxf(am, fmaxf(fmaxf(fabsf(v[i][0]), fabsf(v[i][1])), fmaxf(fabsf(v[i][2]), fabsf(v[i][3])))); }
; #pragma unroll
;     for (int o = 32; o >= 1; o >>= 1) am = fmaxf(am, __shfl_xor(am, o));
;     const float sc = am > 0.f ? 224.f / am : 1.f;
;     u32x4 w;
; #pragma unroll
;     for (int i = 0; i < 4; ++i) {
;       int d = 0;
;       d = __builtin_amdgcn_cvt_pk_fp8_f32(v[i][0] * sc, v[i][1] * sc, d, false);
;       d = __builtin_amdgcn_cvt_pk_fp8_f32(v[i][2] * sc, v[i][3] * sc, d, true);
;       w[i] = (unsigned)d;
;     }
;     *(u32x4*)(q8 + (r < 16384 ? (size_t)r * 2048 : (size_t)(r - 16384) * 2048 + 1024) + lane * 16) = w;
;     if (lane == 0) qs[r] = am > 0.f ? am / 224.f : 1.f;
.Lcv_wd_2:
	v_mov_b32_e32 v10, 0
	v_max3_f32 v10, |v48|, |v49|, v10
	v_max3_f32 v10, |v50|, |v51|, v10
	v_max3_f32 v10, |v52|, |v53|, v10
	v_max3_f32 v10, |v54|, |v55|, v10
	v_max3_f32 v10, |v56|, |v57|, v10
	v_max3_f32 v10, |v58|, |v59|, v10
	v_max3_f32 v10, |v60|, |v61|, v10
	v_max3_f32 v10, |v62|, |v63|, v10
	s_nop 1
	v_max_f32_dpp v11, v10, v10 quad_perm:[1,0,3,2] row_mask:0xf bank_mask:0xf
	s_nop 1
	v_max_f32_dpp v10, v11, v11 quad_perm:[2,3,0,1] row_mask:0xf bank_mask:0xf
	s_nop 1
	v_max_f32_dpp v11, v10, v10 row_half_mirror row_mask:0xf bank_mask:0xf
	s_nop 1
	v_max_f32_dpp v10, v11, v11 row_mirror row_mask:0xf bank_mask:0xf
	s_nop 1
	v_max_f32_dpp v10, v10, v10 row_bcast:15 row_mask:0xa bank_mask:0xf
	s_nop 1
	v_max_f32_dpp v10, v10, v10 row_bcast:31 row_mask:0xc bank_mask:0xf
	s_nop 1
	v_readlane_b32 s50, v10, 63
	s_nop 1
	v_mov_b32_e32 v10, s50
	v_div_scale_f32 v11, s[50:51], v10, v10, v8
	v_rcp_f32_e32 v12, v11
	v_div_scale_f32 v13, vcc, v8, v10, v8
	v_cmp_lt_f32_e64 s[70:71], 0, v10
	v_fma_f32 v14, -v11, v12, 1.0
	v_fmac_f32_e32 v12, v14, v12
	v_mul_f32_e32 v14, v13, v12
	v_fma_f32 v15, -v11, v14, v13
	v_fmac_f32_e32 v14, v15, v12
	v_fma_f32 v13, -v11, v14, v13
	v_div_fmas_f32 v13, v13, v12, v14
	v_div_fixup_f32 v13, v13, v10, v8
	v_cndmask_b32_e64 v13, 1.0, v13, s[70:71]
	v_mul_f32_e32 v48, v48, v13
	v_mul_f32_e32 v49, v49, v13
	v_mul_f32_e32 v50, v50, v13
	v_mul_f32_e32 v51, v51, v13
	v_mul_f32_e32 v52, v52, v13
	v_mul_f32_e32 v53, v53, v13
	v_mul_f32_e32 v54, v54, v13
	v_mul_f32_e32 v55, v55, v13
	v_mul_f32_e32 v56, v56, v13
	v_mul_f32_e32 v57, v57, v13
	v_mul_f32_e32 v58, v58, v13
	v_mul_f32_e32 v59, v59, v13
	v_mul_f32_e32 v60, v60, v13
	v_mul_f32_e32 v61, v61, v13
	v_mul_f32_e32 v62, v62, v13
	v_mul_f32_e32 v63, v63, v13
	v_mov_b32_e32 v4, 0
	v_mov_b32_e32 v5, 0
	v_mov_b32_e32 v6, 0
	v_mov_b32_e32 v7, 0
	v_cvt_pk_fp8_f32 v4, v48, v49
	v_cvt_pk_fp8_f32 v5, v52, v53
	v_cvt_pk_fp8_f32 v6, v56, v57
	v_cvt_pk_fp8_f32 v7, v60, v61
	v_cvt_pk_fp8_f32 v4, v50, v51 op_sel:[0,0,1]
	v_cvt_pk_fp8_f32 v5, v54, v55 op_sel:[0,0,1]
	v_cvt_pk_fp8_f32 v6, v58, v59 op_sel:[0,0,1]
	v_cvt_pk_fp8_f32 v7, v62, v63 op_sel:[0,0,1]
	v_div_scale_f32 v11, s[50:51], v8, v8, v10
	v_rcp_f32_e32 v12, v11
	v_div_scale_f32 v13, vcc, v10, v8, v10
	v_fma_f32 v14, -v11, v12, 1.0
	v_fmac_f32_e32 v12, v14, v12
	v_mul_f32_e32 v14, v13, v12
	v_fma_f32 v15, -v11, v14, v13
	v_fmac_f32_e32 v14, v15, v12
	v_fma_f32 v11, -v11, v14, v13
	v_div_fmas_f32 v11, v11, v12, v14
	v_div_fixup_f32 v11, v11, v8, v10
	v_cndmask_b32_e64 v11, 1.0, v11, s[70:71]
	global_store_dwordx4 v1, v[4:7], s[16:17]
	s_mov_b64 exec, 1
	global_store_dword v9, v11, s[18:19]
	s_mov_b64 exec, -1
	s_add_i32 s68, s40, 0x1680
	s_cmp_lt_u32 s68, 0x8000
	s_cbranch_scc0 .Lcv_nl_2
	s_and_b32 s41, s68, 0x3fff
	s_cmp_lt_u32 s68, 0x4000
	s_cselect_b32 s60, s10, s12
	s_cselect_b32 s61, s11, s13
	s_cselect_b32 s45, 0, 0x400
	s_lshl_b32 s44, s41, 12
	s_add_u32 s60, s60, s44
	s_addc_u32 s61, s61, 0
	s_lshl_b32 s44, s41, 11
	s_add_i32 s44, s44, s45
	s_add_u32 s16, s58, s44
	s_addc_u32 s17, s59, 0
	s_lshl_b32 s44, s68, 2
	s_add_u32 s18, s58, s44
	s_addc_u32 s19, s59, 0
	s_add_u32 s18, s18, 0x2000000
	s_addc_u32 s19, s19, 0
	global_load_dwordx4 v[48:51], v0, s[60:61]
	global_load_dwordx4 v[52:55], v0, s[60:61] offset:16
	global_load_dwordx4 v[56:59], v0, s[60:61] offset:32
	global_load_dwordx4 v[60:63], v0, s[60:61] offset:48
.Lcv_nl_2:
	s_add_i32 s40, s40, 0x780
	s_cmp_lt_u32 s40, 0x8000
	s_cbranch_scc0 .Lcv_done
	s_branch .Lcv_loop
; __device__ __forceinline__ unsigned xb_ld(unsigned* p)              { return __hip_atomic_load(p, __ATOMIC_RELAXED, __HIP_MEMORY_SCOPE_AGENT); }
; __device__ __forceinline__ void grid_barrier(unsigned* bar, unsigned xcc, volatile unsigned* st) {
;   asm volatile("s_waitcnt vmcnt(0)" ::: "memory");
;   __syncthreads();
;   if (threadIdx.x == 0) {
;     __builtin_amdgcn_s_waitcnt(0);
;     unsigned nloc = st[0], nx = st[1];
;     if (nloc == 0u) {
;       const unsigned G = gridDim.x;
;       for (;;) {
;         unsigned sum = 0u, cnt = 0u, mine = 0u;
; #pragma unroll
;         for (unsigned j = 0; j < 16; ++j) { const unsigned c = xb_ld(&bar[XB_XCNT(j)]); sum += c; cnt += (c > 0u) ? 1u : 0u; mine = (j == xcc) ? c : mine; }
;         if (sum == G) { nloc = mine; nx = cnt; break; }
;         __builtin_amdgcn_s_sleep(1);
;       }
;       st[0] = nloc; st[1] = nx;
.Lcv_done:
	s_waitcnt vmcnt(0)
	ds_read_b32 v0, v245 offset:0
	ds_read_b32 v1, v245 offset:1024
	ds_read_b32 v2, v245 offset:2048
	ds_read_b32 v3, v245 offset:3072
	ds_read_b32 v4, v245 offset:4096
	ds_read_b32 v5, v245 offset:5120
	ds_read_b32 v6, v245 offset:6144
	ds_read_b32 v7, v245 offset:7168
	ds_read_b32 v8, v245 offset:8192
	ds_read_b32 v9, v245 offset:9216
	ds_read_b32 v10, v245 offset:10240
	ds_read_b32 v11, v245 offset:11264
	ds_read_b32 v12, v245 offset:12288
	ds_read_b32 v13, v245 offset:13312
	ds_read_b32 v14, v245 offset:14336
	ds_read_b32 v15, v245 offset:15360
	ds_read_b32 v16, v245 offset:16384
	ds_read_b32 v17, v245 offset:17408
	ds_read_b32 v18, v245 offset:18432
	ds_read_b32 v19, v245 offset:19456
	ds_read_b32 v20, v245 offset:20480
	ds_read_b32 v21, v245 offset:21504
	ds_read_b32 v22, v245 offset:22528
	ds_read_b32 v23, v245 offset:23552
	ds_read_b32 v24, v245 offset:24576
	ds_read_b32 v25, v245 offset:25600
	ds_read_b32 v26, v245 offset:26624
	ds_read_b32 v27, v245 offset:27648
	ds_read_b32 v28, v245 offset:28672
	ds_read_b32 v29, v245 offset:29696
	ds_read_b32 v30, v245 offset:30720
	ds_read_b32 v31, v245 offset:31744
	ds_read_b32 v32, v245 offset:32768
	ds_read_b32 v33, v245 offset:33792
	ds_read_b32 v34, v245 offset:34816
	ds_read_b32 v35, v245 offset:35840
	ds_read_b32 v36, v245 offset:36864
	ds_read_b32 v37, v245 offset:37888
	ds_read_b32 v38, v245 offset:38912
	ds_read_b32 v39, v245 offset:39936
	ds_read_b32 v40, v245 offset:40960
	ds_read_b32 v41, v245 offset:41984
	ds_read_b32 v42, v245 offset:43008
	ds_read_b32 v43, v245 offset:44032
	ds_read_b32 v44, v245 offset:45056
	ds_read_b32 v45, v245 offset:46080
	ds_read_b32 v46, v245 offset:47104
	ds_read_b32 v47, v245 offset:48128
	ds_read_b32 v48, v245 offset:49152
	ds_read_b32 v49, v245 offset:50176
	ds_read_b32 v50, v245 offset:51200
	ds_read_b32 v51, v245 offset:52224
	ds_read_b32 v52, v245 offset:53248
	ds_read_b32 v53, v245 offset:54272
	ds_read_b32 v54, v245 offset:55296
	ds_read_b32 v55, v245 offset:56320
	ds_read_b32 v56, v245 offset:57344
	ds_read_b32 v57, v245 offset:58368
	ds_read_b32 v58, v245 offset:59392
	ds_read_b32 v59, v245 offset:60416
	ds_read_b32 v60, v245 offset:61440
	ds_read_b32 v61, v245 offset:62464
	ds_read_b32 v62, v245 offset:63488
	ds_read_b32 v63, v245 offset:64512
	s_waitcnt lgkmcnt(0)
	s_mov_b64 exec, s[66:67]
	v_readlane_b32 s10, v244, 0
	v_readlane_b32 s11, v244, 1
	v_readlane_b32 s12, v244, 2
	v_readlane_b32 s13, v244, 3
	v_readlane_b32 s16, v244, 4
	v_readlane_b32 s17, v244, 5
	v_readlane_b32 s18, v244, 6
	v_readlane_b32 s19, v244, 7
	v_readlane_b32 s40, v244, 8
	v_readlane_b32 s41, v244, 9
	v_readlane_b32 s42, v244, 10
	v_readlane_b32 s43, v244, 11
	v_readlane_b32 s44, v244, 12
	v_readlane_b32 s45, v244, 13
	v_readlane_b32 s46, v244, 14
	v_readlane_b32 s47, v244, 15
	v_readlane_b32 s48, v244, 16
	v_readlane_b32 s49, v244, 17
	v_readlane_b32 s50, v244, 18
	v_readlane_b32 s51, v244, 19
	v_readlane_b32 s58, v244, 20
	v_readlane_b32 s59, v244, 21
	v_readlane_b32 s60, v244, 22
	v_readlane_b32 s61, v244, 23
	v_readlane_b32 s62, v244, 24
	v_readlane_b32 s63, v244, 25
	v_readlane_b32 s64, v244, 26
	v_readlane_b32 s65, v244, 27
	v_readlane_b32 s66, v244, 28
	v_readlane_b32 s67, v244, 29
	v_readlane_b32 s68, v244, 30
	v_readlane_b32 s70, v244, 31
	v_readlane_b32 s71, v244, 32
	v_readlane_b32 vcc_lo, v244, 33
	v_readlane_b32 vcc_hi, v244, 34
	v_readlane_b32 s0, v248, 0
	v_readlane_b32 s1, v248, 1
	s_load_dwordx4 s[24:27], s[0:1], 0xe0
	s_waitcnt lgkmcnt(0)
	s_cmp_gt_i32 s25, 7
	s_cbranch_scc0 .LBB0_862
	s_waitcnt vmcnt(0)
	s_barrier
	s_mov_b64 s[0:1], exec
	v_readlane_b32 s2, v248, 9
	v_readlane_b32 s3, v248, 10
	s_and_b64 s[2:3], s[0:1], s[2:3]
	s_mov_b64 exec, s[2:3]
	s_cbranch_execz .LBB0_861
	s_mov_b64 s[2:3], src_shared_base
	v_mov_b32_e32 v0, 0x12300
	v_mov_b32_e32 v1, s3
	s_waitcnt vmcnt(0) expcnt(0) lgkmcnt(0)
	flat_load_dword v2, v[0:1] sc0 sc1
	s_waitcnt vmcnt(0)
	v_mov_b32_e32 v0, 0x12304
	flat_load_dword v0, v[0:1] sc0 sc1
	s_waitcnt vmcnt(0) lgkmcnt(0)
	v_cmp_eq_u32_e32 vcc, 0, v2
	s_and_saveexec_b64 s[2:3], vcc
	s_cbranch_execz .LBB0_839
	v_readlane_b32 s10, v248, 56
	v_readlane_b32 s11, v248, 57
	s_load_dword s10, s[10:11], 0x0
	v_mov_b32_e32 v1, 0
	v_mov_b32_e32 v2, 0
	s_branch .LBB0_836
